# prep step1: 8 serialized lane-0 beta/log-a blocks vectorized into one block on lanes 0-7 with all loads issued together
# speedup vs baseline: 1.0174x; 1.0174x over previous
.LBB0_449:
	s_waitcnt vmcnt(0)
	v_lshlrev_b32_e32 v128, 16, v53
	v_and_b32_e32 v129, 0xffff0000, v53
	v_lshlrev_b32_e32 v126, 16, v52
	v_and_b32_e32 v127, 0xffff0000, v52
	v_lshlrev_b32_e32 v70, 16, v58
	v_and_b32_e32 v71, 0xffff0000, v58
	v_lshlrev_b32_e32 v52, 16, v65
	v_and_b32_e32 v53, 0xffff0000, v65
	v_lshlrev_b32_e32 v68, 16, v64
	v_and_b32_e32 v69, 0xffff0000, v64
	v_pk_fma_f32 v[64:65], v[42:43], v[128:129], 0 op_sel_hi:[1,1,0]
	v_lshlrev_b32_e32 v124, 16, v51
	v_pk_fma_f32 v[64:65], v[44:45], v[70:71], v[64:65]
	v_and_b32_e32 v125, 0xffff0000, v51
	v_lshlrev_b32_e32 v62, 16, v50
	v_and_b32_e32 v63, 0xffff0000, v50
	v_lshlrev_b32_e32 v50, 16, v66
	v_and_b32_e32 v51, 0xffff0000, v66
	v_lshlrev_b32_e32 v66, 16, v67
	v_and_b32_e32 v67, 0xffff0000, v67
	v_pk_fma_f32 v[64:65], v[46:47], v[68:69], v[64:65]
	v_pk_fma_f32 v[124:125], v[34:35], v[124:125], 0 op_sel_hi:[1,1,0]
	v_pk_fma_f32 v[64:65], v[48:49], v[66:67], v[64:65]
	v_lshlrev_b32_e32 v60, 16, v61
	v_mul_f32_e32 v72, 0xbfb8aa3b, v64
	v_exp_f32_e32 v72, v72
	v_and_b32_e32 v61, 0xffff0000, v61
	v_pk_fma_f32 v[124:125], v[36:37], v[62:63], v[124:125]
	v_lshlrev_b32_e32 v58, 16, v59
	v_add_f32_e32 v72, 1.0, v72
	v_rcp_f32_e32 v128, v72
	v_mul_f32_e32 v72, 0xbfb8aa3b, v65
	v_exp_f32_e32 v72, v72
	v_and_b32_e32 v59, 0xffff0000, v59
	v_pk_fma_f32 v[124:125], v[38:39], v[60:61], v[124:125]
	s_lshl_b32 s0, s0, 2
	v_add_f32_e32 v72, 1.0, v72
	v_pk_fma_f32 v[124:125], v[40:41], v[58:59], v[124:125]
	v_rcp_f32_e32 v129, v72
	v_mul_f32_e32 v72, 0xbfb8aa3b, v124
	v_exp_f32_e32 v72, v72
	s_add_u32 s11, s56, s0
	v_pk_mul_f32 v[64:65], v[64:65], v[128:129]
	s_addc_u32 s54, s57, 0
	v_add_f32_e32 v72, 1.0, v72
	v_rcp_f32_e32 v128, v72
	v_mul_f32_e32 v72, 0xbfb8aa3b, v125
	v_exp_f32_e32 v72, v72
	v_readlane_b32 s1, v253, 41
	s_add_u32 s16, s1, s0
	v_readlane_b32 s1, v253, 42
	v_add_f32_e32 v72, 1.0, v72
	v_rcp_f32_e32 v129, v72
	s_addc_u32 s17, s1, 0
	v_readlane_b32 s1, v253, 43
	s_add_u32 s22, s1, s0
	v_pk_mul_f32 v[124:125], v[124:125], v[128:129]
	v_readlane_b32 s0, v253, 44
	v_pk_mul_f32 v[128:129], v[124:125], v[124:125]
	s_addc_u32 s23, s0, 0
	v_add_f32_e32 v72, v129, v128
	v_lshlrev_b32_e32 v54, 16, v55
	v_and_b32_e32 v55, 0xffff0000, v55
	v_add_f32_dpp v72, v72, v72 quad_perm:[1,0,3,2] row_mask:0xf bank_mask:0xf bound_ctrl:1
	v_cvt_pk_bf16_f32 v64, v64, v65
	ds_write_b32 v21, v64 offset:34816
	v_add_f32_dpp v72, v72, v72 quad_perm:[2,3,0,1] row_mask:0xf bank_mask:0xf bound_ctrl:1
	s_nop 1
	v_add_f32_dpp v72, v72, v72 row_half_mirror row_mask:0xf bank_mask:0xf bound_ctrl:1
	s_nop 1
	v_add_f32_dpp v72, v72, v72 row_mirror row_mask:0xf bank_mask:0xf bound_ctrl:1
	s_nop 0
	v_readlane_b32 s18, v72, 16
	v_readlane_b32 s19, v72, 48
	v_readlane_b32 s0, v72, 0
	v_readlane_b32 s1, v72, 32
	v_mov_b32_e32 v128, s18
	v_mov_b32_e32 v129, s19
	v_pk_add_f32 v[128:129], s[0:1], v[128:129]
	s_nop 0
	v_add_f32_e32 v72, v128, v129
	v_add_f32_e32 v72, 0x358637bd, v72
	v_rsq_f32_e32 v72, v72
	s_nop 0
	v_mul_f32_e32 v72, 0x3db504f3, v72
	v_pk_mul_f32 v[124:125], v[124:125], v[72:73] op_sel_hi:[1,0]
	s_nop 0
	v_cvt_pk_bf16_f32 v123, v124, v125
	v_pk_fma_f32 v[124:125], v[4:5], v[126:127], 0 op_sel_hi:[1,1,0]
	s_nop 0
	v_pk_fma_f32 v[124:125], v[6:7], v[54:55], v[124:125]
	s_nop 0
	v_pk_fma_f32 v[124:125], v[30:31], v[52:53], v[124:125]
	s_nop 0
	v_pk_fma_f32 v[124:125], v[32:33], v[50:51], v[124:125]
	s_nop 0
	v_mul_f32_e32 v72, 0xbfb8aa3b, v124
	v_exp_f32_e32 v72, v72
	s_nop 0
	v_add_f32_e32 v72, 1.0, v72
	v_rcp_f32_e32 v126, v72
	v_mul_f32_e32 v72, 0xbfb8aa3b, v125
	v_exp_f32_e32 v72, v72
	s_nop 0
	v_add_f32_e32 v72, 1.0, v72
	v_rcp_f32_e32 v127, v72
	s_nop 0
	v_pk_mul_f32 v[124:125], v[124:125], v[126:127]
	s_nop 0
	v_pk_mul_f32 v[126:127], v[124:125], v[124:125]
	s_nop 0
	v_add_f32_e32 v72, v127, v126
	s_nop 1
	v_add_f32_dpp v72, v72, v72 quad_perm:[1,0,3,2] row_mask:0xf bank_mask:0xf bound_ctrl:1
	s_nop 1
	v_add_f32_dpp v72, v72, v72 quad_perm:[2,3,0,1] row_mask:0xf bank_mask:0xf bound_ctrl:1
	s_nop 1
	v_add_f32_dpp v72, v72, v72 row_half_mirror row_mask:0xf bank_mask:0xf bound_ctrl:1
	s_nop 1
	v_add_f32_dpp v72, v72, v72 row_mirror row_mask:0xf bank_mask:0xf bound_ctrl:1
	s_nop 0
	v_readlane_b32 s18, v72, 16
	v_readlane_b32 s19, v72, 48
	v_readlane_b32 s0, v72, 0
	v_readlane_b32 s1, v72, 32
	v_mov_b32_e32 v126, s18
	v_mov_b32_e32 v127, s19
	v_pk_add_f32 v[126:127], s[0:1], v[126:127]
	s_nop 0
	v_add_f32_e32 v72, v126, v127
	v_add_f32_e32 v72, 0x358637bd, v72
	v_rsq_f32_e32 v72, v72
	s_nop 0
	v_pk_mul_f32 v[124:125], v[124:125], v[72:73] op_sel_hi:[1,0]
	s_nop 0
	v_cvt_pk_bf16_f32 v72, v124, v125
	ds_write2st64_b32 v21, v72, v123 offset1:68
	s_mov_b64 s[18:19], exec
	s_mov_b32 exec_lo, 0xff
	s_mov_b32 exec_hi, 0
	v_mbcnt_lo_u32_b32 v255, -1, 0
	v_lshlrev_b32_e32 v255, 5, v255
	s_add_u32 s0, s14, s44
	v_readlane_b32 s1, v254, 4
	s_addc_u32 s1, s15, s1
	s_lshl_b64 s[0:1], s[0:1], 5
	s_add_u32 s0, s11, s0
	s_addc_u32 s1, s54, s1
	v_readlane_b32 s55, v254, 12
	global_load_dword v64, v255, s[0:1]
	global_load_dword v126, v157, s[16:17]
	global_load_dword v127, v255, s[0:1] offset:16
	global_load_dword v128, v157, s[22:23]
	s_waitcnt vmcnt(0)
	v_mul_f32_e32 v65, 0xbfb8aa3b, v64
	v_fma_f32 v72, v64, s83, -v65
	v_rndne_f32_e32 v123, v65
	v_fmac_f32_e32 v72, 0xb2a5705f, v64
	v_sub_f32_e32 v65, v65, v123
	v_add_f32_e32 v65, v65, v72
	v_exp_f32_e32 v65, v65
	v_cvt_i32_f32_e32 v72, v123
	v_cmp_nlt_f32_e32 vcc, s43, v64
	v_ldexp_f32 v65, v65, v72
	s_nop 0
	v_cndmask_b32_e32 v65, 0, v65, vcc
	v_cmp_ngt_f32_e32 vcc, s70, v64
	s_nop 1
	v_cndmask_b32_e32 v64, v219, v65, vcc
	v_add_f32_e32 v64, 1.0, v64
	v_div_scale_f32 v65, vcc, v64, v64, 1.0
	v_rcp_f32_e32 v72, v65
	s_nop 0
	v_fma_f32 v123, -v65, v72, 1.0
	v_fmac_f32_e32 v72, v123, v72
	v_div_scale_f32 v123, vcc, 1.0, v64, 1.0
	v_mul_f32_e32 v124, v123, v72
	v_fma_f32 v125, -v65, v124, v123
	v_fmac_f32_e32 v124, v125, v72
	v_fma_f32 v65, -v65, v124, v123
	v_div_fmas_f32 v65, v65, v72, v124
	v_div_fixup_f32 v64, v65, v64, 1.0
	v_lshrrev_b32_e32 v65, 3, v255
	v_add_u32_e32 v65, s55, v65
	ds_write_b32 v65, v64
	v_mov_b32_e32 v64, v126
	v_mul_f32_e32 v65, 0x3fb8aa3b, v64
	v_fma_f32 v72, v64, s71, -v65
	v_rndne_f32_e32 v123, v65
	v_fmac_f32_e32 v72, 0x32a5705f, v64
	v_sub_f32_e32 v65, v65, v123
	v_add_f32_e32 v65, v65, v72
	v_exp_f32_e32 v65, v65
	v_cvt_i32_f32_e32 v72, v123
	v_cmp_ngt_f32_e32 vcc, s74, v64
	v_ldexp_f32 v65, v65, v72
	s_nop 0
	v_cndmask_b32_e32 v65, 0, v65, vcc
	v_cmp_nlt_f32_e32 vcc, s75, v64
	s_nop 1
	v_cndmask_b32_e32 v64, v219, v65, vcc
	v_mov_b32_e32 v65, v127
	v_mov_b32_e32 v72, v128
	v_readlane_b32 s0, v254, 13
	v_add_f32_e32 v72, v65, v72
	v_mul_f32_e64 v123, |v72|, s83
	v_fma_f32 v124, |v72|, s83, -v123
	v_rndne_f32_e32 v125, v123
	v_fma_f32 v124, |v72|, s42, v124
	v_sub_f32_e32 v123, v123, v125
	v_add_f32_e32 v123, v123, v124
	v_exp_f32_e32 v123, v123
	v_cvt_i32_f32_e32 v124, v125
	v_cmp_ngt_f32_e64 vcc, |v72|, s43
	v_max_f32_e32 v65, 0, v72
	v_ldexp_f32 v123, v123, v124
	v_cndmask_b32_e32 v123, 0, v123, vcc
	v_cmp_nlt_f32_e64 vcc, |v72|, s70
	s_nop 1
	v_cndmask_b32_e32 v72, v219, v123, vcc
	v_add_f32_e32 v123, 1.0, v72
	v_add_f32_e32 v124, -1.0, v123
	v_sub_f32_e32 v125, v124, v123
	v_add_f32_e32 v125, 1.0, v125
	v_sub_f32_e32 v124, v72, v124
	v_add_f32_e32 v126, v124, v125
	v_frexp_mant_f32_e32 v124, v123
	v_cmp_gt_f32_e32 vcc, s80, v124
	v_cvt_f64_f32_e32 v[124:125], v123
	v_frexp_exp_i32_f64_e32 v124, v[124:125]
	v_subbrev_co_u32_e32 v124, vcc, 0, v124, vcc
	v_sub_u32_e32 v125, 0, v124
	v_ldexp_f32 v123, v123, v125
	v_ldexp_f32 v125, v126, v125
	v_add_f32_e32 v126, -1.0, v123
	v_add_f32_e32 v127, 1.0, v126
	v_sub_f32_e32 v127, v123, v127
	v_add_f32_e32 v127, v125, v127
	v_add_f32_e32 v128, v126, v127
	v_sub_f32_e32 v126, v126, v128
	v_add_f32_e32 v126, v127, v126
	v_add_f32_e32 v127, 1.0, v123
	v_add_f32_e32 v129, -1.0, v127
	v_sub_f32_e32 v123, v123, v129
	v_add_f32_e32 v123, v125, v123
	v_add_f32_e32 v125, v127, v123
	v_sub_f32_e32 v127, v127, v125
	v_add_f32_e32 v123, v123, v127
	v_rcp_f32_e32 v127, v125
	v_cvt_f32_i32_e32 v124, v124
	v_cmp_neq_f32_e32 vcc, s77, v72
	v_mul_f32_e32 v129, v128, v127
	v_mul_f32_e32 v130, v125, v129
	v_fma_f32 v131, v129, v125, -v130
	v_fmac_f32_e32 v131, v129, v123
	v_add_f32_e32 v132, v130, v131
	v_sub_f32_e32 v133, v128, v132
	v_sub_f32_e32 v128, v128, v133
	v_sub_f32_e32 v130, v132, v130
	v_sub_f32_e32 v128, v128, v132
	v_add_f32_e32 v126, v126, v128
	v_sub_f32_e32 v128, v130, v131
	v_add_f32_e32 v126, v128, v126
	v_add_f32_e32 v128, v133, v126
	v_mul_f32_e32 v130, v127, v128
	v_mul_f32_e32 v131, v125, v130
	v_fma_f32 v125, v130, v125, -v131
	v_fmac_f32_e32 v125, v130, v123
	v_sub_f32_e32 v123, v133, v128
	v_add_f32_e32 v123, v126, v123
	v_add_f32_e32 v126, v131, v125
	v_sub_f32_e32 v132, v128, v126
	v_sub_f32_e32 v128, v128, v132
	v_sub_f32_e32 v131, v126, v131
	v_sub_f32_e32 v126, v128, v126
	v_add_f32_e32 v123, v123, v126
	v_sub_f32_e32 v125, v131, v125
	v_add_f32_e32 v123, v125, v123
	v_add_f32_e32 v125, v129, v130
	v_add_f32_e32 v123, v132, v123
	v_sub_f32_e32 v126, v125, v129
	v_mul_f32_e32 v123, v127, v123
	v_sub_f32_e32 v126, v130, v126
	v_add_f32_e32 v123, v126, v123
	v_mul_f32_e32 v129, 0x3f317218, v124
	v_add_f32_e32 v126, v125, v123
	v_fma_f32 v130, v124, s81, -v129
	v_mul_f32_e32 v127, v126, v126
	v_fmac_f32_e32 v130, 0xb102e308, v124
	v_sub_f32_e32 v124, v126, v125
	v_fmamk_f32 v128, v127, 0x3e9b6dac, v215
	v_sub_f32_e32 v123, v123, v124
	v_add_f32_e32 v124, v129, v130
	v_fmaak_f32 v128, v127, v128, 0x3f2aaada
	v_sub_f32_e32 v125, v124, v129
	v_ldexp_f32 v129, v126, 1
	v_mul_f32_e32 v126, v126, v127
	v_mul_f32_e32 v126, v126, v128
	v_add_f32_e32 v127, v129, v126
	v_sub_f32_e32 v128, v127, v129
	v_ldexp_f32 v123, v123, 1
	v_sub_f32_e32 v126, v126, v128
	v_add_f32_e32 v123, v123, v126
	v_add_f32_e32 v126, v127, v123
	v_sub_f32_e32 v127, v126, v127
	v_sub_f32_e32 v123, v123, v127
	v_add_f32_e32 v127, v124, v126
	v_sub_f32_e32 v128, v127, v124
	v_sub_f32_e32 v129, v127, v128
	v_sub_f32_e32 v125, v130, v125
	v_sub_f32_e32 v124, v124, v129
	v_sub_f32_e32 v126, v126, v128
	v_add_f32_e32 v124, v126, v124
	v_add_f32_e32 v126, v125, v123
	v_sub_f32_e32 v128, v126, v125
	v_sub_f32_e32 v129, v126, v128
	v_sub_f32_e32 v125, v125, v129
	v_sub_f32_e32 v123, v123, v128
	v_add_f32_e32 v124, v126, v124
	v_add_f32_e32 v123, v123, v125
	v_add_f32_e32 v125, v127, v124
	v_sub_f32_e32 v126, v125, v127
	v_sub_f32_e32 v124, v124, v126
	v_add_f32_e32 v123, v123, v124
	v_add_f32_e32 v123, v125, v123
	v_cndmask_b32_e32 v123, v219, v123, vcc
	v_cmp_lt_f32_e64 vcc, |v72|, s94
	s_nop 1
	v_cndmask_b32_e32 v72, v123, v72, vcc
	v_add_f32_e32 v65, v65, v72
	v_mul_f32_e64 v64, v65, -v64
	v_lshrrev_b32_e32 v65, 3, v255
	v_add_u32_e32 v65, s0, v65
	ds_write_b32 v65, v64
.LBB0_451:
	s_or_b64 exec, exec, s[18:19]
	v_pk_fma_f32 v[70:71], v[42:43], v[70:71], 0 op_sel_hi:[1,1,0]
	v_lshlrev_b32_e32 v72, 16, v73
	v_pk_fma_f32 v[70:71], v[44:45], v[68:69], v[70:71]
	v_and_b32_e32 v73, 0xffff0000, v73
	v_pk_fma_f32 v[70:71], v[46:47], v[66:67], v[70:71]
	v_pk_fma_f32 v[62:63], v[34:35], v[62:63], 0 op_sel_hi:[1,1,0]
	v_pk_fma_f32 v[70:71], v[48:49], v[72:73], v[70:71]
	v_pk_fma_f32 v[62:63], v[36:37], v[60:61], v[62:63]
	v_mul_f32_e32 v123, 0xbfb8aa3b, v70
	v_exp_f32_e32 v123, v123
	v_lshlrev_b32_e32 v64, 16, v56
	v_and_b32_e32 v65, 0xffff0000, v56
	v_pk_fma_f32 v[62:63], v[38:39], v[58:59], v[62:63]
	v_add_f32_e32 v123, 1.0, v123
	v_rcp_f32_e32 v124, v123
	v_mul_f32_e32 v123, 0xbfb8aa3b, v71
	v_exp_f32_e32 v123, v123
	v_pk_fma_f32 v[62:63], v[40:41], v[64:65], v[62:63]
	v_pk_fma_f32 v[54:55], v[4:5], v[54:55], 0 op_sel_hi:[1,1,0]
	v_lshlrev_b32_e32 v56, 16, v57
	v_add_f32_e32 v123, 1.0, v123
	v_rcp_f32_e32 v125, v123
	v_mul_f32_e32 v123, 0xbfb8aa3b, v62
	v_exp_f32_e32 v123, v123
	v_pk_fma_f32 v[54:55], v[6:7], v[52:53], v[54:55]
	v_pk_mul_f32 v[70:71], v[70:71], v[124:125]
	v_and_b32_e32 v57, 0xffff0000, v57
	v_add_f32_e32 v123, 1.0, v123
	v_rcp_f32_e32 v124, v123
	v_mul_f32_e32 v123, 0xbfb8aa3b, v63
	v_exp_f32_e32 v123, v123
	v_pk_fma_f32 v[54:55], v[30:31], v[50:51], v[54:55]
	v_add_f32_e32 v123, 1.0, v123
	v_rcp_f32_e32 v125, v123
	v_pk_fma_f32 v[54:55], v[32:33], v[56:57], v[54:55]
	v_pk_mul_f32 v[62:63], v[62:63], v[124:125]
	s_nop 0
	v_pk_mul_f32 v[124:125], v[62:63], v[62:63]
	s_nop 0
	v_add_f32_e32 v123, v125, v124
	s_nop 1
	v_add_f32_dpp v123, v123, v123 quad_perm:[1,0,3,2] row_mask:0xf bank_mask:0xf bound_ctrl:1
	s_nop 1
	v_add_f32_dpp v123, v123, v123 quad_perm:[2,3,0,1] row_mask:0xf bank_mask:0xf bound_ctrl:1
	s_nop 1
	v_add_f32_dpp v123, v123, v123 row_half_mirror row_mask:0xf bank_mask:0xf bound_ctrl:1
	s_nop 1
	v_add_f32_dpp v123, v123, v123 row_mirror row_mask:0xf bank_mask:0xf bound_ctrl:1
	s_nop 0
	v_readlane_b32 s18, v123, 16
	v_readlane_b32 s19, v123, 48
	v_readlane_b32 s0, v123, 0
	v_readlane_b32 s1, v123, 32
	v_mov_b32_e32 v124, s18
	v_mov_b32_e32 v125, s19
	v_pk_add_f32 v[124:125], s[0:1], v[124:125]
	s_nop 0
	v_add_f32_e32 v123, v124, v125
	v_add_f32_e32 v123, 0x358637bd, v123
	v_rsq_f32_e32 v123, v123
	s_nop 0
	v_mul_f32_e32 v124, 0x3db504f3, v123
	v_pk_mul_f32 v[62:63], v[62:63], v[124:125] op_sel_hi:[1,0]
	s_nop 0
	v_cvt_pk_bf16_f32 v123, v62, v63
	v_mul_f32_e32 v62, 0xbfb8aa3b, v54
	v_mul_f32_e32 v63, 0xbfb8aa3b, v55
	v_exp_f32_e32 v62, v62
	v_exp_f32_e32 v63, v63
	v_add_f32_e32 v62, 1.0, v62
	v_add_f32_e32 v63, 1.0, v63
	v_rcp_f32_e32 v62, v62
	v_rcp_f32_e32 v63, v63
	s_nop 0
	v_pk_mul_f32 v[54:55], v[54:55], v[62:63]
	s_nop 0
	v_pk_mul_f32 v[62:63], v[54:55], v[54:55]
	s_nop 0
	v_add_f32_e32 v62, v63, v62
	s_nop 1
	v_add_f32_dpp v62, v62, v62 quad_perm:[1,0,3,2] row_mask:0xf bank_mask:0xf bound_ctrl:1
	s_nop 1
	v_add_f32_dpp v62, v62, v62 quad_perm:[2,3,0,1] row_mask:0xf bank_mask:0xf bound_ctrl:1
	s_nop 1
	v_add_f32_dpp v62, v62, v62 row_half_mirror row_mask:0xf bank_mask:0xf bound_ctrl:1
	s_nop 1
	v_add_f32_dpp v62, v62, v62 row_mirror row_mask:0xf bank_mask:0xf bound_ctrl:1
	s_nop 0
	v_readlane_b32 s18, v62, 16
	v_readlane_b32 s19, v62, 48
	v_readlane_b32 s0, v62, 0
	v_readlane_b32 s1, v62, 32
	v_mov_b32_e32 v62, s18
	v_mov_b32_e32 v63, s19
	v_pk_add_f32 v[62:63], s[0:1], v[62:63]
	s_nop 0
	v_add_f32_e32 v62, v62, v63
	v_add_f32_e32 v62, 0x358637bd, v62
	v_rsq_f32_e32 v62, v62
	s_nop 0
	v_pk_mul_f32 v[54:55], v[54:55], v[62:63] op_sel_hi:[1,0]
	s_nop 0
	v_cvt_pk_bf16_f32 v54, v54, v55
	ds_write2st64_b32 v74, v54, v123 offset1:68
	v_cvt_pk_bf16_f32 v54, v70, v71
	ds_write_b32 v74, v54 offset:34816
	v_pk_fma_f32 v[68:69], v[42:43], v[68:69], 0 op_sel_hi:[1,1,0]
	v_lshlrev_b32_e32 v70, 16, v121
	v_pk_fma_f32 v[68:69], v[44:45], v[66:67], v[68:69]
	v_and_b32_e32 v71, 0xffff0000, v121
	v_pk_fma_f32 v[68:69], v[46:47], v[72:73], v[68:69]
	v_lshlrev_b32_e32 v62, 16, v120
	v_pk_fma_f32 v[68:69], v[48:49], v[70:71], v[68:69]
	v_and_b32_e32 v63, 0xffff0000, v120
	v_mul_f32_e32 v120, 0xbfb8aa3b, v68
	v_mul_f32_e32 v121, 0xbfb8aa3b, v69
	v_exp_f32_e32 v120, v120
	v_exp_f32_e32 v121, v121
	v_pk_fma_f32 v[60:61], v[34:35], v[60:61], 0 op_sel_hi:[1,1,0]
	v_pk_fma_f32 v[52:53], v[4:5], v[52:53], 0 op_sel_hi:[1,1,0]
	v_add_f32_e32 v120, 1.0, v120
	v_add_f32_e32 v121, 1.0, v121
	v_rcp_f32_e32 v120, v120
	v_rcp_f32_e32 v121, v121
	v_pk_fma_f32 v[60:61], v[36:37], v[58:59], v[60:61]
	v_pk_fma_f32 v[52:53], v[6:7], v[50:51], v[52:53]
	v_pk_fma_f32 v[60:61], v[38:39], v[64:65], v[60:61]
	v_pk_mul_f32 v[68:69], v[68:69], v[120:121]
	v_pk_fma_f32 v[60:61], v[40:41], v[62:63], v[60:61]
	v_lshlrev_b32_e32 v54, 16, v122
	v_mul_f32_e32 v120, 0xbfb8aa3b, v60
	v_mul_f32_e32 v121, 0xbfb8aa3b, v61
	v_exp_f32_e32 v120, v120
	v_exp_f32_e32 v121, v121
	v_and_b32_e32 v55, 0xffff0000, v122
	v_pk_fma_f32 v[52:53], v[30:31], v[56:57], v[52:53]
	v_add_f32_e32 v120, 1.0, v120
	v_add_f32_e32 v121, 1.0, v121
	v_rcp_f32_e32 v120, v120
	v_rcp_f32_e32 v121, v121
	v_pk_fma_f32 v[52:53], v[32:33], v[54:55], v[52:53]
	v_pk_mul_f32 v[60:61], v[60:61], v[120:121]
	s_nop 0
	v_pk_mul_f32 v[120:121], v[60:61], v[60:61]
	s_nop 0
	v_add_f32_e32 v120, v121, v120
	s_nop 1
	v_add_f32_dpp v120, v120, v120 quad_perm:[1,0,3,2] row_mask:0xf bank_mask:0xf bound_ctrl:1
	s_nop 1
	v_add_f32_dpp v120, v120, v120 quad_perm:[2,3,0,1] row_mask:0xf bank_mask:0xf bound_ctrl:1
	s_nop 1
	v_add_f32_dpp v120, v120, v120 row_half_mirror row_mask:0xf bank_mask:0xf bound_ctrl:1
	s_nop 1
	v_add_f32_dpp v120, v120, v120 row_mirror row_mask:0xf bank_mask:0xf bound_ctrl:1
	s_nop 0
	v_readlane_b32 s18, v120, 16
	v_readlane_b32 s19, v120, 48
	v_readlane_b32 s0, v120, 0
	v_readlane_b32 s1, v120, 32
	v_mov_b32_e32 v120, s18
	v_mov_b32_e32 v121, s19
	v_pk_add_f32 v[120:121], s[0:1], v[120:121]
	s_nop 0
	v_add_f32_e32 v120, v120, v121
	v_add_f32_e32 v120, 0x358637bd, v120
	v_rsq_f32_e32 v120, v120
	s_nop 0
	v_mul_f32_e32 v120, 0x3db504f3, v120
	v_pk_mul_f32 v[60:61], v[60:61], v[120:121] op_sel_hi:[1,0]
	s_nop 0
	v_cvt_pk_bf16_f32 v120, v60, v61
	v_mul_f32_e32 v60, 0xbfb8aa3b, v52
	v_mul_f32_e32 v61, 0xbfb8aa3b, v53
	v_exp_f32_e32 v60, v60
	v_exp_f32_e32 v61, v61
	v_add_f32_e32 v60, 1.0, v60
	v_add_f32_e32 v61, 1.0, v61
	v_rcp_f32_e32 v60, v60
	v_rcp_f32_e32 v61, v61
	s_nop 0
	v_pk_mul_f32 v[52:53], v[52:53], v[60:61]
	s_nop 0
	v_pk_mul_f32 v[60:61], v[52:53], v[52:53]
	s_nop 0
	v_add_f32_e32 v60, v61, v60
	s_nop 1
	v_add_f32_dpp v60, v60, v60 quad_perm:[1,0,3,2] row_mask:0xf bank_mask:0xf bound_ctrl:1
	s_nop 1
	v_add_f32_dpp v60, v60, v60 quad_perm:[2,3,0,1] row_mask:0xf bank_mask:0xf bound_ctrl:1
	s_nop 1
	v_add_f32_dpp v60, v60, v60 row_half_mirror row_mask:0xf bank_mask:0xf bound_ctrl:1
	s_nop 1
	v_add_f32_dpp v60, v60, v60 row_mirror row_mask:0xf bank_mask:0xf bound_ctrl:1
	s_nop 0
	v_readlane_b32 s18, v60, 16
	v_readlane_b32 s19, v60, 48
	v_readlane_b32 s0, v60, 0
	v_readlane_b32 s1, v60, 32
	v_mov_b32_e32 v60, s18
	v_mov_b32_e32 v61, s19
	v_pk_add_f32 v[60:61], s[0:1], v[60:61]
	s_nop 0
	v_add_f32_e32 v60, v60, v61
	v_add_f32_e32 v60, 0x358637bd, v60
	v_rsq_f32_e32 v60, v60
	s_nop 0
	v_pk_mul_f32 v[52:53], v[52:53], v[60:61] op_sel_hi:[1,0]
	s_nop 0
	v_cvt_pk_bf16_f32 v52, v52, v53
	ds_write2st64_b32 v75, v52, v120 offset1:68
	v_cvt_pk_bf16_f32 v52, v68, v69
	ds_write_b32 v75, v52 offset:34816
	v_pk_fma_f32 v[66:67], v[42:43], v[66:67], 0 op_sel_hi:[1,1,0]
	v_lshlrev_b32_e32 v68, 16, v117
	v_pk_fma_f32 v[66:67], v[44:45], v[72:73], v[66:67]
	v_and_b32_e32 v69, 0xffff0000, v117
	v_pk_fma_f32 v[66:67], v[46:47], v[70:71], v[66:67]
	v_lshlrev_b32_e32 v60, 16, v118
	v_pk_fma_f32 v[66:67], v[48:49], v[68:69], v[66:67]
	v_and_b32_e32 v61, 0xffff0000, v118
	v_mul_f32_e32 v117, 0xbfb8aa3b, v66
	v_exp_f32_e32 v117, v117
	v_pk_fma_f32 v[58:59], v[34:35], v[58:59], 0 op_sel_hi:[1,1,0]
	v_lshlrev_b32_e32 v52, 16, v119
	v_pk_fma_f32 v[58:59], v[36:37], v[64:65], v[58:59]
	v_add_f32_e32 v117, 1.0, v117
	v_rcp_f32_e32 v118, v117
	v_mul_f32_e32 v117, 0xbfb8aa3b, v67
	v_exp_f32_e32 v117, v117
	v_pk_fma_f32 v[58:59], v[38:39], v[62:63], v[58:59]
	v_and_b32_e32 v53, 0xffff0000, v119
	v_pk_fma_f32 v[58:59], v[40:41], v[60:61], v[58:59]
	v_add_f32_e32 v117, 1.0, v117
	v_rcp_f32_e32 v119, v117
	v_mul_f32_e32 v117, 0xbfb8aa3b, v58
	v_exp_f32_e32 v117, v117
	v_pk_fma_f32 v[50:51], v[4:5], v[50:51], 0 op_sel_hi:[1,1,0]
	v_pk_mul_f32 v[66:67], v[66:67], v[118:119]
	v_pk_fma_f32 v[50:51], v[6:7], v[56:57], v[50:51]
	v_add_f32_e32 v117, 1.0, v117
	v_rcp_f32_e32 v118, v117
	v_mul_f32_e32 v117, 0xbfb8aa3b, v59
	v_exp_f32_e32 v117, v117
	v_pk_fma_f32 v[50:51], v[30:31], v[54:55], v[50:51]
	v_add_f32_e32 v117, 1.0, v117
	v_rcp_f32_e32 v119, v117
	v_pk_fma_f32 v[50:51], v[32:33], v[52:53], v[50:51]
	v_pk_mul_f32 v[58:59], v[58:59], v[118:119]
	s_nop 0
	v_pk_mul_f32 v[118:119], v[58:59], v[58:59]
	s_nop 0
	v_add_f32_e32 v117, v119, v118
	s_nop 1
	v_add_f32_dpp v117, v117, v117 quad_perm:[1,0,3,2] row_mask:0xf bank_mask:0xf bound_ctrl:1
	s_nop 1
	v_add_f32_dpp v117, v117, v117 quad_perm:[2,3,0,1] row_mask:0xf bank_mask:0xf bound_ctrl:1
	s_nop 1
	v_add_f32_dpp v117, v117, v117 row_half_mirror row_mask:0xf bank_mask:0xf bound_ctrl:1
	s_nop 1
	v_add_f32_dpp v117, v117, v117 row_mirror row_mask:0xf bank_mask:0xf bound_ctrl:1
	s_nop 0
	v_readlane_b32 s18, v117, 16
	v_readlane_b32 s19, v117, 48
	v_readlane_b32 s0, v117, 0
	v_readlane_b32 s1, v117, 32
	v_mov_b32_e32 v118, s18
	v_mov_b32_e32 v119, s19
	v_pk_add_f32 v[118:119], s[0:1], v[118:119]
	s_nop 0
	v_add_f32_e32 v117, v118, v119
	v_add_f32_e32 v117, 0x358637bd, v117
	v_rsq_f32_e32 v117, v117
	s_nop 0
	v_mul_f32_e32 v118, 0x3db504f3, v117
	v_pk_mul_f32 v[58:59], v[58:59], v[118:119] op_sel_hi:[1,0]
	s_nop 0
	v_cvt_pk_bf16_f32 v117, v58, v59
	v_mul_f32_e32 v58, 0xbfb8aa3b, v50
	v_mul_f32_e32 v59, 0xbfb8aa3b, v51
	v_exp_f32_e32 v58, v58
	v_exp_f32_e32 v59, v59
	v_add_f32_e32 v58, 1.0, v58
	v_add_f32_e32 v59, 1.0, v59
	v_rcp_f32_e32 v58, v58
	v_rcp_f32_e32 v59, v59
	s_nop 0
	v_pk_mul_f32 v[50:51], v[50:51], v[58:59]
	s_nop 0
	v_pk_mul_f32 v[58:59], v[50:51], v[50:51]
	s_nop 0
	v_add_f32_e32 v58, v59, v58
	s_nop 1
	v_add_f32_dpp v58, v58, v58 quad_perm:[1,0,3,2] row_mask:0xf bank_mask:0xf bound_ctrl:1
	s_nop 1
	v_add_f32_dpp v58, v58, v58 quad_perm:[2,3,0,1] row_mask:0xf bank_mask:0xf bound_ctrl:1
	s_nop 1
	v_add_f32_dpp v58, v58, v58 row_half_mirror row_mask:0xf bank_mask:0xf bound_ctrl:1
	s_nop 1
	v_add_f32_dpp v58, v58, v58 row_mirror row_mask:0xf bank_mask:0xf bound_ctrl:1
	s_nop 0
	v_readlane_b32 s18, v58, 16
	v_readlane_b32 s19, v58, 48
	v_readlane_b32 s0, v58, 0
	v_readlane_b32 s1, v58, 32
	v_mov_b32_e32 v58, s18
	v_mov_b32_e32 v59, s19
	v_pk_add_f32 v[58:59], s[0:1], v[58:59]
	s_nop 0
	v_add_f32_e32 v58, v58, v59
	v_add_f32_e32 v58, 0x358637bd, v58
	v_rsq_f32_e32 v58, v58
	s_nop 0
	v_pk_mul_f32 v[50:51], v[50:51], v[58:59] op_sel_hi:[1,0]
	s_nop 0
	v_cvt_pk_bf16_f32 v50, v50, v51
	ds_write2st64_b32 v76, v50, v117 offset1:68
	v_cvt_pk_bf16_f32 v50, v66, v67
	ds_write_b32 v76, v50 offset:34816
	v_pk_fma_f32 v[72:73], v[42:43], v[72:73], 0 op_sel_hi:[1,1,0]
	v_lshlrev_b32_e32 v66, 16, v115
	v_pk_fma_f32 v[72:73], v[44:45], v[70:71], v[72:73]
	v_and_b32_e32 v67, 0xffff0000, v115
	v_pk_fma_f32 v[72:73], v[46:47], v[68:69], v[72:73]
	v_lshlrev_b32_e32 v58, 16, v114
	v_pk_fma_f32 v[72:73], v[48:49], v[66:67], v[72:73]
	v_and_b32_e32 v59, 0xffff0000, v114
	v_mul_f32_e32 v114, 0xbfb8aa3b, v72
	v_mul_f32_e32 v115, 0xbfb8aa3b, v73
	v_exp_f32_e32 v114, v114
	v_exp_f32_e32 v115, v115
	v_pk_fma_f32 v[64:65], v[34:35], v[64:65], 0 op_sel_hi:[1,1,0]
	v_pk_fma_f32 v[56:57], v[4:5], v[56:57], 0 op_sel_hi:[1,1,0]
	v_add_f32_e32 v114, 1.0, v114
	v_add_f32_e32 v115, 1.0, v115
	v_rcp_f32_e32 v114, v114
	v_rcp_f32_e32 v115, v115
	v_pk_fma_f32 v[64:65], v[36:37], v[62:63], v[64:65]
	v_pk_fma_f32 v[56:57], v[6:7], v[54:55], v[56:57]
	v_pk_fma_f32 v[64:65], v[38:39], v[60:61], v[64:65]
	v_pk_mul_f32 v[72:73], v[72:73], v[114:115]
	v_pk_fma_f32 v[64:65], v[40:41], v[58:59], v[64:65]
	v_lshlrev_b32_e32 v50, 16, v116
	v_mul_f32_e32 v114, 0xbfb8aa3b, v64
	v_mul_f32_e32 v115, 0xbfb8aa3b, v65
	v_exp_f32_e32 v114, v114
	v_exp_f32_e32 v115, v115
	v_and_b32_e32 v51, 0xffff0000, v116
	v_pk_fma_f32 v[56:57], v[30:31], v[52:53], v[56:57]
	v_add_f32_e32 v114, 1.0, v114
	v_add_f32_e32 v115, 1.0, v115
	v_rcp_f32_e32 v114, v114
	v_rcp_f32_e32 v115, v115
	v_pk_fma_f32 v[56:57], v[32:33], v[50:51], v[56:57]
	v_pk_mul_f32 v[64:65], v[64:65], v[114:115]
	s_nop 0
	v_pk_mul_f32 v[114:115], v[64:65], v[64:65]
	s_nop 0
	v_add_f32_e32 v114, v115, v114
	s_nop 1
	v_add_f32_dpp v114, v114, v114 quad_perm:[1,0,3,2] row_mask:0xf bank_mask:0xf bound_ctrl:1
	s_nop 1
	v_add_f32_dpp v114, v114, v114 quad_perm:[2,3,0,1] row_mask:0xf bank_mask:0xf bound_ctrl:1
	s_nop 1
	v_add_f32_dpp v114, v114, v114 row_half_mirror row_mask:0xf bank_mask:0xf bound_ctrl:1
	s_nop 1
	v_add_f32_dpp v114, v114, v114 row_mirror row_mask:0xf bank_mask:0xf bound_ctrl:1
	s_nop 0
	v_readlane_b32 s18, v114, 16
	v_readlane_b32 s19, v114, 48
	v_readlane_b32 s0, v114, 0
	v_readlane_b32 s1, v114, 32
	v_mov_b32_e32 v114, s18
	v_mov_b32_e32 v115, s19
	v_pk_add_f32 v[114:115], s[0:1], v[114:115]
	s_nop 0
	v_add_f32_e32 v114, v114, v115
	v_add_f32_e32 v114, 0x358637bd, v114
	v_rsq_f32_e32 v114, v114
	s_nop 0
	v_mul_f32_e32 v114, 0x3db504f3, v114
	v_pk_mul_f32 v[64:65], v[64:65], v[114:115] op_sel_hi:[1,0]
	s_nop 0
	v_cvt_pk_bf16_f32 v114, v64, v65
	v_mul_f32_e32 v64, 0xbfb8aa3b, v56
	v_mul_f32_e32 v65, 0xbfb8aa3b, v57
	v_exp_f32_e32 v64, v64
	v_exp_f32_e32 v65, v65
	v_add_f32_e32 v64, 1.0, v64
	v_add_f32_e32 v65, 1.0, v65
	v_rcp_f32_e32 v64, v64
	v_rcp_f32_e32 v65, v65
	s_nop 0
	v_pk_mul_f32 v[56:57], v[56:57], v[64:65]
	s_nop 0
	v_pk_mul_f32 v[64:65], v[56:57], v[56:57]
	s_nop 0
	v_add_f32_e32 v64, v65, v64
	s_nop 1
	v_add_f32_dpp v64, v64, v64 quad_perm:[1,0,3,2] row_mask:0xf bank_mask:0xf bound_ctrl:1
	s_nop 1
	v_add_f32_dpp v64, v64, v64 quad_perm:[2,3,0,1] row_mask:0xf bank_mask:0xf bound_ctrl:1
	s_nop 1
	v_add_f32_dpp v64, v64, v64 row_half_mirror row_mask:0xf bank_mask:0xf bound_ctrl:1
	s_nop 1
	v_add_f32_dpp v64, v64, v64 row_mirror row_mask:0xf bank_mask:0xf bound_ctrl:1
	s_nop 0
	v_readlane_b32 s18, v64, 16
	v_readlane_b32 s19, v64, 48
	v_readlane_b32 s0, v64, 0
	v_readlane_b32 s1, v64, 32
	v_mov_b32_e32 v64, s18
	v_mov_b32_e32 v65, s19
	v_pk_add_f32 v[64:65], s[0:1], v[64:65]
	s_nop 0
	v_add_f32_e32 v64, v64, v65
	v_add_f32_e32 v64, 0x358637bd, v64
	v_rsq_f32_e32 v64, v64
	s_nop 0
	v_pk_mul_f32 v[56:57], v[56:57], v[64:65] op_sel_hi:[1,0]
	s_nop 0
	v_cvt_pk_bf16_f32 v56, v56, v57
	ds_write2st64_b32 v77, v56, v114 offset1:68
	v_cvt_pk_bf16_f32 v56, v72, v73
	ds_write_b32 v77, v56 offset:34816
	v_pk_fma_f32 v[70:71], v[42:43], v[70:71], 0 op_sel_hi:[1,1,0]
	v_lshlrev_b32_e32 v72, 16, v111
	v_pk_fma_f32 v[70:71], v[44:45], v[68:69], v[70:71]
	v_and_b32_e32 v73, 0xffff0000, v111
	v_pk_fma_f32 v[70:71], v[46:47], v[66:67], v[70:71]
	v_lshlrev_b32_e32 v64, 16, v112
	v_pk_fma_f32 v[70:71], v[48:49], v[72:73], v[70:71]
	v_and_b32_e32 v65, 0xffff0000, v112
	v_mul_f32_e32 v111, 0xbfb8aa3b, v70
	v_exp_f32_e32 v111, v111
	v_pk_fma_f32 v[62:63], v[34:35], v[62:63], 0 op_sel_hi:[1,1,0]
	v_lshlrev_b32_e32 v56, 16, v113
	v_pk_fma_f32 v[62:63], v[36:37], v[60:61], v[62:63]
	v_add_f32_e32 v111, 1.0, v111
	v_rcp_f32_e32 v112, v111
	v_mul_f32_e32 v111, 0xbfb8aa3b, v71
	v_exp_f32_e32 v111, v111
	v_pk_fma_f32 v[62:63], v[38:39], v[58:59], v[62:63]
	v_and_b32_e32 v57, 0xffff0000, v113
	v_pk_fma_f32 v[62:63], v[40:41], v[64:65], v[62:63]
	v_add_f32_e32 v111, 1.0, v111
	v_rcp_f32_e32 v113, v111
	v_mul_f32_e32 v111, 0xbfb8aa3b, v62
	v_exp_f32_e32 v111, v111
	v_pk_fma_f32 v[54:55], v[4:5], v[54:55], 0 op_sel_hi:[1,1,0]
	v_pk_mul_f32 v[70:71], v[70:71], v[112:113]
	v_pk_fma_f32 v[54:55], v[6:7], v[52:53], v[54:55]
	v_add_f32_e32 v111, 1.0, v111
	v_rcp_f32_e32 v112, v111
	v_mul_f32_e32 v111, 0xbfb8aa3b, v63
	v_exp_f32_e32 v111, v111
	v_pk_fma_f32 v[54:55], v[30:31], v[50:51], v[54:55]
	v_add_f32_e32 v111, 1.0, v111
	v_rcp_f32_e32 v113, v111
	v_pk_fma_f32 v[54:55], v[32:33], v[56:57], v[54:55]
	v_pk_mul_f32 v[62:63], v[62:63], v[112:113]
	s_nop 0
	v_pk_mul_f32 v[112:113], v[62:63], v[62:63]
	s_nop 0
	v_add_f32_e32 v111, v113, v112
	s_nop 1
	v_add_f32_dpp v111, v111, v111 quad_perm:[1,0,3,2] row_mask:0xf bank_mask:0xf bound_ctrl:1
	s_nop 1
	v_add_f32_dpp v111, v111, v111 quad_perm:[2,3,0,1] row_mask:0xf bank_mask:0xf bound_ctrl:1
	s_nop 1
	v_add_f32_dpp v111, v111, v111 row_half_mirror row_mask:0xf bank_mask:0xf bound_ctrl:1
	s_nop 1
	v_add_f32_dpp v111, v111, v111 row_mirror row_mask:0xf bank_mask:0xf bound_ctrl:1
	s_nop 0
	v_readlane_b32 s18, v111, 16
	v_readlane_b32 s19, v111, 48
	v_readlane_b32 s0, v111, 0
	v_readlane_b32 s1, v111, 32
	v_mov_b32_e32 v112, s18
	v_mov_b32_e32 v113, s19
	v_pk_add_f32 v[112:113], s[0:1], v[112:113]
	s_nop 0
	v_add_f32_e32 v111, v112, v113
	v_add_f32_e32 v111, 0x358637bd, v111
	v_rsq_f32_e32 v111, v111
	s_nop 0
	v_mul_f32_e32 v112, 0x3db504f3, v111
	v_pk_mul_f32 v[62:63], v[62:63], v[112:113] op_sel_hi:[1,0]
	s_nop 0
	v_cvt_pk_bf16_f32 v111, v62, v63
	v_mul_f32_e32 v62, 0xbfb8aa3b, v54
	v_mul_f32_e32 v63, 0xbfb8aa3b, v55
	v_exp_f32_e32 v62, v62
	v_exp_f32_e32 v63, v63
	v_add_f32_e32 v62, 1.0, v62
	v_add_f32_e32 v63, 1.0, v63
	v_rcp_f32_e32 v62, v62
	v_rcp_f32_e32 v63, v63
	s_nop 0
	v_pk_mul_f32 v[54:55], v[54:55], v[62:63]
	s_nop 0
	v_pk_mul_f32 v[62:63], v[54:55], v[54:55]
	s_nop 0
	v_add_f32_e32 v62, v63, v62
	s_nop 1
	v_add_f32_dpp v62, v62, v62 quad_perm:[1,0,3,2] row_mask:0xf bank_mask:0xf bound_ctrl:1
	s_nop 1
	v_add_f32_dpp v62, v62, v62 quad_perm:[2,3,0,1] row_mask:0xf bank_mask:0xf bound_ctrl:1
	s_nop 1
	v_add_f32_dpp v62, v62, v62 row_half_mirror row_mask:0xf bank_mask:0xf bound_ctrl:1
	s_nop 1
	v_add_f32_dpp v62, v62, v62 row_mirror row_mask:0xf bank_mask:0xf bound_ctrl:1
	s_nop 0
	v_readlane_b32 s18, v62, 16
	v_readlane_b32 s19, v62, 48
	v_readlane_b32 s0, v62, 0
	v_readlane_b32 s1, v62, 32
	v_mov_b32_e32 v62, s18
	v_mov_b32_e32 v63, s19
	v_pk_add_f32 v[62:63], s[0:1], v[62:63]
	s_nop 0
	v_add_f32_e32 v62, v62, v63
	v_add_f32_e32 v62, 0x358637bd, v62
	v_rsq_f32_e32 v62, v62
	s_nop 0
	v_pk_mul_f32 v[54:55], v[54:55], v[62:63] op_sel_hi:[1,0]
	s_nop 0
	v_cvt_pk_bf16_f32 v54, v54, v55
	ds_write2st64_b32 v78, v54, v111 offset1:68
	v_cvt_pk_bf16_f32 v54, v70, v71
	ds_write_b32 v78, v54 offset:34816
	v_pk_fma_f32 v[68:69], v[42:43], v[68:69], 0 op_sel_hi:[1,1,0]
	v_lshlrev_b32_e32 v70, 16, v109
	v_pk_fma_f32 v[68:69], v[44:45], v[66:67], v[68:69]
	v_and_b32_e32 v71, 0xffff0000, v109
	v_pk_fma_f32 v[68:69], v[46:47], v[72:73], v[68:69]
	v_lshlrev_b32_e32 v62, 16, v108
	v_pk_fma_f32 v[68:69], v[48:49], v[70:71], v[68:69]
	v_and_b32_e32 v63, 0xffff0000, v108
	v_mul_f32_e32 v108, 0xbfb8aa3b, v68
	v_mul_f32_e32 v109, 0xbfb8aa3b, v69
	v_exp_f32_e32 v108, v108
	v_exp_f32_e32 v109, v109
	v_pk_fma_f32 v[60:61], v[34:35], v[60:61], 0 op_sel_hi:[1,1,0]
	v_pk_fma_f32 v[52:53], v[4:5], v[52:53], 0 op_sel_hi:[1,1,0]
	v_add_f32_e32 v108, 1.0, v108
	v_add_f32_e32 v109, 1.0, v109
	v_rcp_f32_e32 v108, v108
	v_rcp_f32_e32 v109, v109
	v_pk_fma_f32 v[60:61], v[36:37], v[58:59], v[60:61]
	v_pk_fma_f32 v[52:53], v[6:7], v[50:51], v[52:53]
	v_pk_fma_f32 v[60:61], v[38:39], v[64:65], v[60:61]
	v_pk_mul_f32 v[68:69], v[68:69], v[108:109]
	v_pk_fma_f32 v[60:61], v[40:41], v[62:63], v[60:61]
	v_lshlrev_b32_e32 v54, 16, v110
	v_mul_f32_e32 v108, 0xbfb8aa3b, v60
	v_mul_f32_e32 v109, 0xbfb8aa3b, v61
	v_exp_f32_e32 v108, v108
	v_exp_f32_e32 v109, v109
	v_and_b32_e32 v55, 0xffff0000, v110
	v_pk_fma_f32 v[52:53], v[30:31], v[56:57], v[52:53]
	v_add_f32_e32 v108, 1.0, v108
	v_add_f32_e32 v109, 1.0, v109
	v_rcp_f32_e32 v108, v108
	v_rcp_f32_e32 v109, v109
	v_pk_fma_f32 v[52:53], v[32:33], v[54:55], v[52:53]
	v_pk_mul_f32 v[60:61], v[60:61], v[108:109]
	s_nop 0
	v_pk_mul_f32 v[108:109], v[60:61], v[60:61]
	s_nop 0
	v_add_f32_e32 v108, v109, v108
	s_nop 1
	v_add_f32_dpp v108, v108, v108 quad_perm:[1,0,3,2] row_mask:0xf bank_mask:0xf bound_ctrl:1
	s_nop 1
	v_add_f32_dpp v108, v108, v108 quad_perm:[2,3,0,1] row_mask:0xf bank_mask:0xf bound_ctrl:1
	s_nop 1
	v_add_f32_dpp v108, v108, v108 row_half_mirror row_mask:0xf bank_mask:0xf bound_ctrl:1
	s_nop 1
	v_add_f32_dpp v108, v108, v108 row_mirror row_mask:0xf bank_mask:0xf bound_ctrl:1
	s_nop 0
	v_readlane_b32 s18, v108, 16
	v_readlane_b32 s19, v108, 48
	v_readlane_b32 s0, v108, 0
	v_readlane_b32 s1, v108, 32
	v_mov_b32_e32 v108, s18
	v_mov_b32_e32 v109, s19
	v_pk_add_f32 v[108:109], s[0:1], v[108:109]
	s_nop 0
	v_add_f32_e32 v108, v108, v109
	v_add_f32_e32 v108, 0x358637bd, v108
	v_rsq_f32_e32 v108, v108
	s_nop 0
	v_mul_f32_e32 v108, 0x3db504f3, v108
	v_pk_mul_f32 v[60:61], v[60:61], v[108:109] op_sel_hi:[1,0]
	s_nop 0
	v_cvt_pk_bf16_f32 v108, v60, v61
	v_mul_f32_e32 v60, 0xbfb8aa3b, v52
	v_mul_f32_e32 v61, 0xbfb8aa3b, v53
	v_exp_f32_e32 v60, v60
	v_exp_f32_e32 v61, v61
	v_add_f32_e32 v60, 1.0, v60
	v_add_f32_e32 v61, 1.0, v61
	v_rcp_f32_e32 v60, v60
	v_rcp_f32_e32 v61, v61
	s_nop 0
	v_pk_mul_f32 v[52:53], v[52:53], v[60:61]
	s_nop 0
	v_pk_mul_f32 v[60:61], v[52:53], v[52:53]
	s_nop 0
	v_add_f32_e32 v60, v61, v60
	s_nop 1
	v_add_f32_dpp v60, v60, v60 quad_perm:[1,0,3,2] row_mask:0xf bank_mask:0xf bound_ctrl:1
	s_nop 1
	v_add_f32_dpp v60, v60, v60 quad_perm:[2,3,0,1] row_mask:0xf bank_mask:0xf bound_ctrl:1
	s_nop 1
	v_add_f32_dpp v60, v60, v60 row_half_mirror row_mask:0xf bank_mask:0xf bound_ctrl:1
	s_nop 1
	v_add_f32_dpp v60, v60, v60 row_mirror row_mask:0xf bank_mask:0xf bound_ctrl:1
	s_nop 0
	v_readlane_b32 s18, v60, 16
	v_readlane_b32 s19, v60, 48
	v_readlane_b32 s0, v60, 0
	v_readlane_b32 s1, v60, 32
	v_mov_b32_e32 v60, s18
	v_mov_b32_e32 v61, s19
	v_pk_add_f32 v[60:61], s[0:1], v[60:61]
	s_nop 0
	v_add_f32_e32 v60, v60, v61
	v_add_f32_e32 v60, 0x358637bd, v60
	v_rsq_f32_e32 v60, v60
	s_nop 0
	v_pk_mul_f32 v[52:53], v[52:53], v[60:61] op_sel_hi:[1,0]
	s_nop 0
	v_cvt_pk_bf16_f32 v52, v52, v53
	ds_write2st64_b32 v79, v52, v108 offset1:68
	v_cvt_pk_bf16_f32 v52, v68, v69
	ds_write_b32 v79, v52 offset:34816
	v_pk_fma_f32 v[34:35], v[34:35], v[58:59], 0 op_sel_hi:[1,1,0]
	v_lshlrev_b32_e32 v52, 16, v106
	v_pk_fma_f32 v[34:35], v[36:37], v[64:65], v[34:35]
	v_and_b32_e32 v53, 0xffff0000, v106
	v_pk_fma_f32 v[34:35], v[38:39], v[62:63], v[34:35]
	v_lshlrev_b32_e32 v38, 16, v29
	v_pk_fma_f32 v[34:35], v[40:41], v[52:53], v[34:35]
	v_and_b32_e32 v39, 0xffff0000, v29
	v_mul_f32_e32 v36, 0xbfb8aa3b, v34
	v_mul_f32_e32 v37, 0xbfb8aa3b, v35
	v_exp_f32_e32 v36, v36
	v_exp_f32_e32 v37, v37
	v_pk_fma_f32 v[4:5], v[4:5], v[50:51], 0 op_sel_hi:[1,1,0]
	v_pk_fma_f32 v[42:43], v[42:43], v[66:67], 0 op_sel_hi:[1,1,0]
	v_add_f32_e32 v36, 1.0, v36
	v_add_f32_e32 v37, 1.0, v37
	v_rcp_f32_e32 v36, v36
	v_rcp_f32_e32 v37, v37
	v_pk_fma_f32 v[4:5], v[6:7], v[56:57], v[4:5]
	v_pk_fma_f32 v[42:43], v[44:45], v[72:73], v[42:43]
	v_pk_fma_f32 v[4:5], v[30:31], v[54:55], v[4:5]
	v_pk_mul_f32 v[34:35], v[34:35], v[36:37]
	v_pk_fma_f32 v[4:5], v[32:33], v[38:39], v[4:5]
	v_pk_mul_f32 v[36:37], v[34:35], v[34:35]
	v_mul_f32_e32 v6, 0xbfb8aa3b, v4
	v_add_f32_e32 v29, v37, v36
	v_lshlrev_b32_e32 v60, 16, v107
	v_and_b32_e32 v61, 0xffff0000, v107
	v_add_f32_dpp v29, v29, v29 quad_perm:[1,0,3,2] row_mask:0xf bank_mask:0xf bound_ctrl:1
	v_pk_fma_f32 v[42:43], v[46:47], v[70:71], v[42:43]
	s_nop 0
	v_add_f32_dpp v29, v29, v29 quad_perm:[2,3,0,1] row_mask:0xf bank_mask:0xf bound_ctrl:1
	v_pk_fma_f32 v[42:43], v[48:49], v[60:61], v[42:43]
	s_nop 0
	v_add_f32_dpp v29, v29, v29 row_half_mirror row_mask:0xf bank_mask:0xf bound_ctrl:1
	v_mul_f32_e32 v44, 0xbfb8aa3b, v42
	v_mul_f32_e32 v45, 0xbfb8aa3b, v43
	v_add_f32_dpp v29, v29, v29 row_mirror row_mask:0xf bank_mask:0xf bound_ctrl:1
	v_exp_f32_e32 v44, v44
	v_readlane_b32 s0, v29, 0
	v_readlane_b32 s18, v29, 16
	v_readlane_b32 s1, v29, 32
	v_readlane_b32 s19, v29, 48
	v_exp_f32_e32 v29, v6
	v_mul_f32_e32 v6, 0xbfb8aa3b, v5
	v_exp_f32_e32 v31, v6
	v_mov_b32_e32 v36, s18
	v_add_f32_e32 v29, 1.0, v29
	v_rcp_f32_e32 v30, v29
	v_add_f32_e32 v29, 1.0, v31
	v_rcp_f32_e32 v31, v29
	v_mov_b32_e32 v37, s19
	v_pk_add_f32 v[6:7], s[0:1], v[36:37]
	v_exp_f32_e32 v45, v45
	v_add_f32_e32 v6, v6, v7
	v_add_f32_e32 v6, 0x358637bd, v6
	v_pk_mul_f32 v[4:5], v[4:5], v[30:31]
	v_rsq_f32_e32 v29, v6
	v_pk_mul_f32 v[6:7], v[4:5], v[4:5]
	v_add_f32_e32 v44, 1.0, v44
	v_add_f32_e32 v6, v7, v6
	v_add_f32_e32 v45, 1.0, v45
	v_rcp_f32_e32 v44, v44
	v_add_f32_dpp v6, v6, v6 quad_perm:[1,0,3,2] row_mask:0xf bank_mask:0xf bound_ctrl:1
	v_rcp_f32_e32 v45, v45
	v_mul_f32_e32 v30, 0x3db504f3, v29
	v_add_f32_dpp v6, v6, v6 quad_perm:[2,3,0,1] row_mask:0xf bank_mask:0xf bound_ctrl:1
	v_pk_mul_f32 v[30:31], v[34:35], v[30:31] op_sel_hi:[1,0]
	v_pk_mul_f32 v[40:41], v[42:43], v[44:45]
	v_add_f32_dpp v6, v6, v6 row_half_mirror row_mask:0xf bank_mask:0xf bound_ctrl:1
	s_nop 1
	v_add_f32_dpp v6, v6, v6 row_mirror row_mask:0xf bank_mask:0xf bound_ctrl:1
	s_nop 0
	v_readlane_b32 s18, v6, 16
	v_readlane_b32 s19, v6, 48
	v_readlane_b32 s0, v6, 0
	v_readlane_b32 s1, v6, 32
	v_mov_b32_e32 v6, s18
	v_mov_b32_e32 v7, s19
	v_pk_add_f32 v[6:7], s[0:1], v[6:7]
	s_nop 0
	v_add_f32_e32 v6, v6, v7
	v_add_f32_e32 v6, 0x358637bd, v6
	v_rsq_f32_e32 v6, v6
	v_cvt_pk_bf16_f32 v7, v30, v31
	v_pk_mul_f32 v[4:5], v[4:5], v[6:7] op_sel_hi:[1,0]
	s_nop 0
	v_cvt_pk_bf16_f32 v4, v4, v5
	ds_write2st64_b32 v80, v4, v7 offset1:68
	v_cvt_pk_bf16_f32 v4, v40, v41
	ds_write_b32 v80, v4 offset:34816
	s_waitcnt lgkmcnt(0)
	s_barrier
	v_readlane_b32 s0, v253, 45
	v_readlane_b32 s1, v253, 46
	s_andn2_b64 vcc, exec, s[0:1]
	s_cbranch_vccnz .LBB0_467
	ds_read_b32 v4, v15
	v_and_b32_e32 v5, 64, v217
	v_add_u32_e32 v6, -1, v217
	v_cmp_lt_i32_e32 vcc, v6, v5
	v_add_u32_e32 v7, -2, v217
	v_readlane_b32 s0, v254, 34
	v_cndmask_b32_e32 v6, v6, v217, vcc
	v_lshlrev_b32_e32 v6, 2, v6
	s_waitcnt lgkmcnt(0)
	ds_bpermute_b32 v6, v6, v4
	v_cmp_lt_i32_e32 vcc, v7, v5
	v_readlane_b32 s1, v254, 35
	s_waitcnt lgkmcnt(0)
	v_add_f32_e32 v6, v4, v6
	v_cndmask_b32_e32 v7, v7, v217, vcc
	v_cndmask_b32_e64 v4, v6, v4, s[40:41]
	v_lshlrev_b32_e32 v6, 2, v7
	ds_bpermute_b32 v6, v6, v4
	v_add_u32_e32 v7, -4, v217
	v_cmp_lt_i32_e32 vcc, v7, v5
	s_waitcnt lgkmcnt(0)
	v_add_f32_e32 v6, v4, v6
	v_cndmask_b32_e32 v7, v7, v217, vcc
	v_cndmask_b32_e64 v4, v6, v4, s[0:1]
	v_lshlrev_b32_e32 v6, 2, v7
	ds_bpermute_b32 v6, v6, v4
	v_add_u32_e32 v7, -8, v217
	v_cmp_lt_i32_e32 vcc, v7, v5
	v_readlane_b32 s0, v254, 36
	v_readlane_b32 s1, v254, 37
	v_cndmask_b32_e32 v7, v7, v217, vcc
	s_waitcnt lgkmcnt(0)
	v_add_f32_e32 v6, v4, v6
	v_cndmask_b32_e64 v4, v6, v4, s[0:1]
	v_lshlrev_b32_e32 v6, 2, v7
	ds_bpermute_b32 v6, v6, v4
	v_add_u32_e32 v7, -16, v217
	v_cmp_lt_i32_e32 vcc, v7, v5
	v_readlane_b32 s0, v254, 38
	v_readlane_b32 s1, v254, 39
	v_cndmask_b32_e32 v7, v7, v217, vcc
	s_waitcnt lgkmcnt(0)
	v_add_f32_e32 v6, v4, v6
	v_cndmask_b32_e64 v4, v6, v4, s[0:1]
	v_lshlrev_b32_e32 v6, 2, v7
	ds_bpermute_b32 v6, v6, v4
	v_subrev_u32_e32 v7, 32, v217
	v_cmp_lt_i32_e32 vcc, v7, v5
	v_readlane_b32 s0, v254, 40
	v_readlane_b32 s1, v254, 41
	v_cndmask_b32_e32 v5, v7, v217, vcc
	s_waitcnt lgkmcnt(0)
	v_add_f32_e32 v6, v4, v6
	v_cndmask_b32_e64 v4, v6, v4, s[0:1]
	v_lshlrev_b32_e32 v5, 2, v5
	ds_bpermute_b32 v5, v5, v4
	v_readlane_b32 s0, v254, 42
	v_readlane_b32 s1, v254, 43
	s_waitcnt lgkmcnt(0)
	v_add_f32_e32 v5, v4, v5
	v_cndmask_b32_e64 v4, v5, v4, s[0:1]
	v_mul_f32_e32 v5, 0x3fb8aa3b, v4
	v_fma_f32 v6, v4, s71, -v5
	v_rndne_f32_e32 v7, v5
	v_fmac_f32_e32 v6, 0x32a5705f, v4
	v_sub_f32_e32 v5, v5, v7
	v_add_f32_e32 v5, v5, v6
	v_cvt_i32_f32_e32 v7, v7
	v_exp_f32_e32 v5, v5
	v_cmp_ngt_f32_e32 vcc, s74, v4
	ds_write_b32 v17, v4
	v_ldexp_f32 v5, v5, v7
	v_cndmask_b32_e32 v5, 0, v5, vcc
	v_cmp_nlt_f32_e32 vcc, s75, v4
	s_nop 1
	v_cndmask_b32_e32 v4, v219, v5, vcc
	ds_write_b32 v19, v4

	.amdhsa_kernel _Z14fwd_megakernel6Params
		.amdhsa_group_segment_fixed_size 0
		.amdhsa_private_segment_fixed_size 0
		.amdhsa_kernarg_size 440
		.amdhsa_user_sgpr_count 2
		.amdhsa_user_sgpr_dispatch_ptr 0
		.amdhsa_user_sgpr_queue_ptr 0
		.amdhsa_user_sgpr_kernarg_segment_ptr 1
		.amdhsa_user_sgpr_dispatch_id 0
		.amdhsa_user_sgpr_kernarg_preload_length 0
		.amdhsa_user_sgpr_kernarg_preload_offset 0
		.amdhsa_user_sgpr_private_segment_size 0
		.amdhsa_uses_dynamic_stack 0
		.amdhsa_enable_private_segment 0
		.amdhsa_system_sgpr_workgroup_id_x 1
		.amdhsa_system_sgpr_workgroup_id_y 0
		.amdhsa_system_sgpr_workgroup_id_z 0
		.amdhsa_system_sgpr_workgroup_info 0
		.amdhsa_system_vgpr_workitem_id 2
		.amdhsa_next_free_vgpr 256
		.amdhsa_next_free_sgpr 100
		.amdhsa_accum_offset 256
		.amdhsa_reserve_vcc 1
		.amdhsa_float_round_mode_32 0
		.amdhsa_float_round_mode_16_64 0
		.amdhsa_float_denorm_mode_32 3
		.amdhsa_float_denorm_mode_16_64 3
		.amdhsa_dx10_clamp 1
		.amdhsa_ieee_mode 1
		.amdhsa_fp16_overflow 0
		.amdhsa_tg_split 0
		.amdhsa_exception_fp_ieee_invalid_op 0
		.amdhsa_exception_fp_denorm_src 0
		.amdhsa_exception_fp_ieee_div_zero 0
		.amdhsa_exception_fp_ieee_overflow 0
		.amdhsa_exception_fp_ieee_underflow 0
		.amdhsa_exception_fp_ieee_inexact 0
		.amdhsa_exception_int_div_zero 0
	.end_amdhsa_kernel

amdhsa.kernels:
  - .agpr_count:     0
    .args:
      - .offset:         0
        .size:           184
        .value_kind:     by_value
      - .offset:         184
        .size:           4
        .value_kind:     hidden_block_count_x
      - .offset:         188
        .size:           4
        .value_kind:     hidden_block_count_y
      - .offset:         192
        .size:           4
        .value_kind:     hidden_block_count_z
      - .offset:         196
        .size:           2
        .value_kind:     hidden_group_size_x
      - .offset:         198
        .size:           2
        .value_kind:     hidden_group_size_y
      - .offset:         200
        .size:           2
        .value_kind:     hidden_group_size_z
      - .offset:         202
        .size:           2
        .value_kind:     hidden_remainder_x
      - .offset:         204
        .size:           2
        .value_kind:     hidden_remainder_y
      - .offset:         206
        .size:           2
        .value_kind:     hidden_remainder_z
      - .offset:         224
        .size:           8
        .value_kind:     hidden_global_offset_x
      - .offset:         232
        .size:           8
        .value_kind:     hidden_global_offset_y
      - .offset:         240
        .size:           8
        .value_kind:     hidden_global_offset_z
      - .offset:         248
        .size:           2
        .value_kind:     hidden_grid_dims
      - .offset:         272
        .size:           8
        .value_kind:     hidden_multigrid_sync_arg
      - .offset:         304
        .size:           4
        .value_kind:     hidden_dynamic_lds_size
    .group_segment_fixed_size: 0
    .kernarg_segment_align: 8
    .kernarg_segment_size: 440
    .language:       OpenCL C
    .language_version:
      - 2
      - 0
    .max_flat_workgroup_size: 512
    .name:           _Z14fwd_megakernel6Params
    .private_segment_fixed_size: 0
    .sgpr_count:     106
    .sgpr_spill_count: 423
    .symbol:         _Z14fwd_megakernel6Params.kd
    .uniform_work_group_size: 1
    .uses_dynamic_stack: false
    .vgpr_count:     256
    .vgpr_spill_count: 0
    .wavefront_size: 64
